# v108 + K-loop loads 4/4/3/5: last LDS-DMA load of segment 3 issued at the head of segment 4, segment-3 wait vmcnt(7)
# speedup vs baseline: 1.0048x; 1.0048x over previous
; #define PG8_STAGE(bufoff, gbase, voff) do { _Pragma("unroll") for (int _i = 0; _i < 2; ++_i) \
;         __builtin_amdgcn_global_load_lds((const unsigned*)((const char*)(gbase) + (voff)[_i]), (PG8_LAS unsigned*)(lds + (bufoff) + ldsw + _i * 8192), 16, 0, 0); } while (0)
; #define PG8_LDA(dst, b, h) do { _Pragma("unroll") for (int m = 0; m < 4; ++m) _Pragma("unroll") for (int k = 0; k < 2; ++k) dst[m][k] = *(const PG8_LAS bf16x8*)(lds + PG8_SA(b, h) + aoff + m * 2048 + k * 1024); } while (0)
; #define PG8_LDB(dst, b, h) do { _Pragma("unroll") for (int n = 0; n < 2; ++n) _Pragma("unroll") for (int k = 0; k < 2; ++k) dst[n][k] = *(const PG8_LAS bf16x8*)(lds + PG8_SB(b, h) + boff + n * 2048 + k * 1024); } while (0)
; #define PG8_MMA(ai, bj, At, Bt) do { __builtin_amdgcn_s_setprio(1); _Pragma("unroll") for (int m = 0; m < 4; ++m) _Pragma("unroll") for (int n = 0; n < 2; ++n) _Pragma("unroll") for (int k = 0; k < 2; ++k) \
;         acc[ai][bj][m][n] = __builtin_amdgcn_mfma_f32_16x16x32_bf16(Bt[n][k], At[m][k], acc[ai][bj][m][n], 0, 0, 0); __builtin_amdgcn_s_setprio(0); } while (0)
; #define PG8_WAIT_V(n) asm volatile("s_waitcnt vmcnt(" #n ")" ::: "memory")
; #define PG8_WAIT_L(n) asm volatile("s_waitcnt lgkmcnt(" #n ")" ::: "memory")
; #define PG8_BAR __builtin_amdgcn_s_barrier()
; #define PG8_SCHED __builtin_amdgcn_sched_barrier(0)
; template <class Epi, class Sched, bool ALIGN_EPI = false, bool SP2 = false>
; __device__ __forceinline__ void gemm_phase(PG8_LAS unsigned char* lds, const Gemm g, const Sched& S, const Epi& E) {
;     ...
;             PG8_LDB(B0, 1, 0); PG8_LDB(B1, 1, 1); PG8_SCHED; PG8_LDA(At, 1, 0); PG8_STAGE(PG8_SA(0, 1), a2 + hstep, voffA);
;             PG8_WAIT_V(8); PG8_WAIT_L(0); PG8_BAR; PG8_MMA(0, 0, At, B0); PG8_MMA(0, 1, At, B1); PG8_BAR; PG8_SCHED;
;             PG8_LDA(At, 1, 1); PG8_STAGE(PG8_SB(1, 0), b3, voffB); PG8_STAGE(PG8_SB(1, 1), b3 + hstep, voffB); PG8_STAGE(PG8_SA(1, 0), a3, voffA);
;             PG8_WAIT_V(8); PG8_WAIT_L(0); PG8_BAR; PG8_MMA(1, 0, At, B0); PG8_MMA(1, 1, At, B1); PG8_BAR; PG8_SCHED;
.Lkmid_0:
	ds_read_b128 v[132:135], v204 offset:32768
	ds_read_b128 v[136:139], v204 offset:33792
	ds_read_b128 v[140:143], v204 offset:34816
	ds_read_b128 v[144:147], v204 offset:35840
	ds_read_b128 v[148:151], v204 offset:49152
	ds_read_b128 v[152:155], v204 offset:50176
	ds_read_b128 v[156:159], v204 offset:51200
	ds_read_b128 v[160:163], v204 offset:52224
	s_mov_b32 m0, s42
	s_add_u32 s30, s30, 0x40000
	s_addc_u32 s31, s31, 0
	global_load_lds_dwordx4 v[224:225], off
	s_mov_b32 m0, s43
	v_lshl_add_u64 v[228:229], s[30:31], 0, v[0:1]
	global_load_lds_dwordx4 v[226:227], off
	s_mov_b32 m0, s46
	ds_read_b128 v[164:167], v205 offset:32768
	ds_read_b128 v[182:185], v205 offset:33792
	ds_read_b128 v[186:189], v205 offset:34816
	ds_read_b128 v[190:193], v205 offset:35840
	ds_read_b128 v[208:211], v205 offset:36864
	ds_read_b128 v[212:215], v205 offset:37888
	ds_read_b128 v[216:219], v205 offset:38912
	ds_read_b128 v[220:223], v205 offset:39936
	global_load_lds_dwordx4 v[228:229], off
	s_waitcnt vmcnt(7) lgkmcnt(0)
	s_barrier
	s_setprio 1
	v_mfma_f32_16x16x32_bf16 v[128:131], v[132:135], v[164:167], v[128:131]
	v_mfma_f32_16x16x32_bf16 v[124:127], v[140:143], v[164:167], v[124:127]
	v_mfma_f32_16x16x32_bf16 v[112:115], v[132:135], v[186:189], v[112:115]
	v_mfma_f32_16x16x32_bf16 v[108:111], v[140:143], v[186:189], v[108:111]
	v_mfma_f32_16x16x32_bf16 v[96:99], v[132:135], v[208:211], v[96:99]
	v_mfma_f32_16x16x32_bf16 v[92:95], v[140:143], v[208:211], v[92:95]
	v_mfma_f32_16x16x32_bf16 v[80:83], v[132:135], v[216:219], v[80:83]
	v_mfma_f32_16x16x32_bf16 v[76:79], v[140:143], v[216:219], v[76:79]
	v_mfma_f32_16x16x32_bf16 v[128:131], v[136:139], v[182:185], v[128:131]
	v_mfma_f32_16x16x32_bf16 v[124:127], v[144:147], v[182:185], v[124:127]
	v_mfma_f32_16x16x32_bf16 v[112:115], v[136:139], v[190:193], v[112:115]
	v_mfma_f32_16x16x32_bf16 v[108:111], v[144:147], v[190:193], v[108:111]
	v_mfma_f32_16x16x32_bf16 v[96:99], v[136:139], v[212:215], v[96:99]
	v_mfma_f32_16x16x32_bf16 v[92:95], v[144:147], v[212:215], v[92:95]
	v_mfma_f32_16x16x32_bf16 v[80:83], v[136:139], v[220:223], v[80:83]
	v_mfma_f32_16x16x32_bf16 v[76:79], v[144:147], v[220:223], v[76:79]
	s_setprio 0
	s_setprio 1
	v_mfma_f32_16x16x32_bf16 v[120:123], v[148:151], v[164:167], v[120:123]
	v_mfma_f32_16x16x32_bf16 v[116:119], v[156:159], v[164:167], v[116:119]
	v_mfma_f32_16x16x32_bf16 v[104:107], v[148:151], v[186:189], v[104:107]
	v_mfma_f32_16x16x32_bf16 v[100:103], v[156:159], v[186:189], v[100:103]
	v_mfma_f32_16x16x32_bf16 v[88:91], v[148:151], v[208:211], v[88:91]
	v_mfma_f32_16x16x32_bf16 v[84:87], v[156:159], v[208:211], v[84:87]
	v_mfma_f32_16x16x32_bf16 v[72:75], v[148:151], v[216:219], v[72:75]
	v_mfma_f32_16x16x32_bf16 v[68:71], v[156:159], v[216:219], v[68:71]
	v_mfma_f32_16x16x32_bf16 v[120:123], v[152:155], v[182:185], v[120:123]
	v_mfma_f32_16x16x32_bf16 v[116:119], v[160:163], v[182:185], v[116:119]
	v_mfma_f32_16x16x32_bf16 v[104:107], v[152:155], v[190:193], v[104:107]
	v_mfma_f32_16x16x32_bf16 v[100:103], v[160:163], v[190:193], v[100:103]
	v_mfma_f32_16x16x32_bf16 v[88:91], v[152:155], v[212:215], v[88:91]
	v_mfma_f32_16x16x32_bf16 v[84:87], v[160:163], v[212:215], v[84:87]
	v_mfma_f32_16x16x32_bf16 v[72:75], v[152:155], v[220:223], v[72:75]
	v_mfma_f32_16x16x32_bf16 v[68:71], v[160:163], v[220:223], v[68:71]
	s_setprio 0
	s_barrier
	s_mov_b32 m0, s47
	v_lshl_add_u64 v[228:229], s[30:31], 0, v[170:171]
	global_load_lds_dwordx4 v[228:229], off
	s_add_i32 m0, s41, 0x17f80
	ds_read_b128 v[164:167], v205 offset:49152
	ds_read_b128 v[182:185], v205 offset:50176
	ds_read_b128 v[186:189], v205 offset:51200
	ds_read_b128 v[190:193], v205 offset:52224
	ds_read_b128 v[208:211], v205 offset:53248
	ds_read_b128 v[212:215], v205 offset:54272
	ds_read_b128 v[216:219], v205 offset:55296
	ds_read_b128 v[220:223], v205 offset:56320
	global_load_lds_dwordx4 v[194:195], off offset:128
	s_add_i32 m0, s41, 0x19f80
	s_add_u32 s8, s8, 0x100
	s_addc_u32 s9, s9, 0
	global_load_lds_dwordx4 v[202:203], off offset:128
	s_add_i32 m0, s41, 0x1bf80
	s_add_u32 s23, s23, 0x100
	s_addc_u32 s44, s44, 0
	global_load_lds_dwordx4 v[244:245], off offset:128
	s_add_i32 m0, s41, 0x1df80
	s_cmp_eq_u32 s45, 12
	global_load_lds_dwordx4 v[246:247], off offset:128
	s_cbranch_scc0 .Lks4_0
	s_add_i32 m0, s50, 0xffffff80
	s_nop 0
	global_load_lds_dwordx4 v[224:225], off offset:128
	s_add_i32 m0, s51, 0xffffff80
	s_nop 0
	global_load_lds_dwordx4 v[226:227], off offset:128

; #define PG8_STAGE(bufoff, gbase, voff) do { _Pragma("unroll") for (int _i = 0; _i < 2; ++_i) \
;         __builtin_amdgcn_global_load_lds((const unsigned*)((const char*)(gbase) + (voff)[_i]), (PG8_LAS unsigned*)(lds + (bufoff) + ldsw + _i * 8192), 16, 0, 0); } while (0)
; #define PG8_LDA(dst, b, h) do { _Pragma("unroll") for (int m = 0; m < 4; ++m) _Pragma("unroll") for (int k = 0; k < 2; ++k) dst[m][k] = *(const PG8_LAS bf16x8*)(lds + PG8_SA(b, h) + aoff + m * 2048 + k * 1024); } while (0)
; #define PG8_LDB(dst, b, h) do { _Pragma("unroll") for (int n = 0; n < 2; ++n) _Pragma("unroll") for (int k = 0; k < 2; ++k) dst[n][k] = *(const PG8_LAS bf16x8*)(lds + PG8_SB(b, h) + boff + n * 2048 + k * 1024); } while (0)
; #define PG8_MMA(ai, bj, At, Bt) do { __builtin_amdgcn_s_setprio(1); _Pragma("unroll") for (int m = 0; m < 4; ++m) _Pragma("unroll") for (int n = 0; n < 2; ++n) _Pragma("unroll") for (int k = 0; k < 2; ++k) \
;         acc[ai][bj][m][n] = __builtin_amdgcn_mfma_f32_16x16x32_bf16(Bt[n][k], At[m][k], acc[ai][bj][m][n], 0, 0, 0); __builtin_amdgcn_s_setprio(0); } while (0)
; #define PG8_WAIT_V(n) asm volatile("s_waitcnt vmcnt(" #n ")" ::: "memory")
; #define PG8_WAIT_L(n) asm volatile("s_waitcnt lgkmcnt(" #n ")" ::: "memory")
; #define PG8_BAR __builtin_amdgcn_s_barrier()
; #define PG8_SCHED __builtin_amdgcn_sched_barrier(0)
; template <class Epi, class Sched, bool ALIGN_EPI = false, bool SP2 = false>
; __device__ __forceinline__ void gemm_phase(PG8_LAS unsigned char* lds, const Gemm g, const Sched& S, const Epi& E) {
;     ...
;             PG8_LDB(B0, 1, 0); PG8_LDB(B1, 1, 1); PG8_SCHED; PG8_LDA(At, 1, 0); PG8_STAGE(PG8_SA(0, 1), a2 + hstep, voffA);
;             PG8_WAIT_V(8); PG8_WAIT_L(0); PG8_BAR; PG8_MMA(0, 0, At, B0); PG8_MMA(0, 1, At, B1); PG8_BAR; PG8_SCHED;
;             PG8_LDA(At, 1, 1); PG8_STAGE(PG8_SB(1, 0), b3, voffB); PG8_STAGE(PG8_SB(1, 1), b3 + hstep, voffB); PG8_STAGE(PG8_SA(1, 0), a3, voffA);
;             PG8_WAIT_V(8); PG8_WAIT_L(0); PG8_BAR; PG8_MMA(1, 0, At, B0); PG8_MMA(1, 1, At, B1); PG8_BAR; PG8_SCHED;
.Lkmid_1:
	ds_read_b128 v[108:111], v251 offset:32768
	ds_read_b128 v[112:115], v251 offset:33792
	ds_read_b128 v[124:127], v251 offset:34816
	ds_read_b128 v[128:131], v251 offset:35840
	ds_read_b128 v[132:135], v251 offset:49152
	ds_read_b128 v[140:143], v251 offset:50176
	ds_read_b128 v[148:151], v251 offset:51200
	ds_read_b128 v[156:159], v251 offset:52224
	s_mov_b32 m0, s42
	s_add_u32 s34, s34, 0x40000
	s_addc_u32 s35, s35, 0
	global_load_lds_dwordx4 v[216:217], off
	s_mov_b32 m0, s43
	v_lshl_add_u64 v[220:221], s[34:35], 0, v[0:1]
	global_load_lds_dwordx4 v[218:219], off
	s_mov_b32 m0, s46
	ds_read_b128 v[164:167], v253 offset:32768
	ds_read_b128 v[168:171], v253 offset:33792
	ds_read_b128 v[172:175], v253 offset:34816
	ds_read_b128 v[176:179], v253 offset:35840
	ds_read_b128 v[180:183], v253 offset:36864
	ds_read_b128 v[184:187], v253 offset:37888
	ds_read_b128 v[188:191], v253 offset:38912
	ds_read_b128 v[192:195], v253 offset:39936
	global_load_lds_dwordx4 v[220:221], off
	s_waitcnt vmcnt(7) lgkmcnt(0)
	s_barrier
	s_setprio 1
	v_mfma_f32_16x16x32_bf16 v[160:163], v[108:111], v[164:167], v[160:163]
	v_mfma_f32_16x16x32_bf16 v[152:155], v[124:127], v[164:167], v[152:155]
	v_mfma_f32_16x16x32_bf16 v[120:123], v[108:111], v[172:175], v[120:123]
	v_mfma_f32_16x16x32_bf16 v[116:119], v[124:127], v[172:175], v[116:119]
	v_mfma_f32_16x16x32_bf16 v[96:99], v[108:111], v[180:183], v[96:99]
	v_mfma_f32_16x16x32_bf16 v[92:95], v[124:127], v[180:183], v[92:95]
	v_mfma_f32_16x16x32_bf16 v[80:83], v[108:111], v[188:191], v[80:83]
	v_mfma_f32_16x16x32_bf16 v[76:79], v[124:127], v[188:191], v[76:79]
	v_mfma_f32_16x16x32_bf16 v[160:163], v[112:115], v[168:171], v[160:163]
	v_mfma_f32_16x16x32_bf16 v[152:155], v[128:131], v[168:171], v[152:155]
	v_mfma_f32_16x16x32_bf16 v[120:123], v[112:115], v[176:179], v[120:123]
	v_mfma_f32_16x16x32_bf16 v[116:119], v[128:131], v[176:179], v[116:119]
	v_mfma_f32_16x16x32_bf16 v[96:99], v[112:115], v[184:187], v[96:99]
	v_mfma_f32_16x16x32_bf16 v[92:95], v[128:131], v[184:187], v[92:95]
	v_mfma_f32_16x16x32_bf16 v[80:83], v[112:115], v[192:195], v[80:83]
	v_mfma_f32_16x16x32_bf16 v[76:79], v[128:131], v[192:195], v[76:79]
	s_setprio 0
	s_setprio 1
	v_mfma_f32_16x16x32_bf16 v[144:147], v[132:135], v[164:167], v[144:147]
	v_mfma_f32_16x16x32_bf16 v[136:139], v[148:151], v[164:167], v[136:139]
	v_mfma_f32_16x16x32_bf16 v[104:107], v[132:135], v[172:175], v[104:107]
	v_mfma_f32_16x16x32_bf16 v[100:103], v[148:151], v[172:175], v[100:103]
	v_mfma_f32_16x16x32_bf16 v[88:91], v[132:135], v[180:183], v[88:91]
	v_mfma_f32_16x16x32_bf16 v[84:87], v[148:151], v[180:183], v[84:87]
	v_mfma_f32_16x16x32_bf16 v[72:75], v[132:135], v[188:191], v[72:75]
	v_mfma_f32_16x16x32_bf16 v[68:71], v[148:151], v[188:191], v[68:71]
	v_mfma_f32_16x16x32_bf16 v[144:147], v[140:143], v[168:171], v[144:147]
	v_mfma_f32_16x16x32_bf16 v[136:139], v[156:159], v[168:171], v[136:139]
	v_mfma_f32_16x16x32_bf16 v[104:107], v[140:143], v[176:179], v[104:107]
	v_mfma_f32_16x16x32_bf16 v[100:103], v[156:159], v[176:179], v[100:103]
	v_mfma_f32_16x16x32_bf16 v[88:91], v[140:143], v[184:187], v[88:91]
	v_mfma_f32_16x16x32_bf16 v[84:87], v[156:159], v[184:187], v[84:87]
	v_mfma_f32_16x16x32_bf16 v[72:75], v[140:143], v[192:195], v[72:75]
	v_mfma_f32_16x16x32_bf16 v[68:71], v[156:159], v[192:195], v[68:71]
	s_setprio 0
	s_barrier
	s_mov_b32 m0, s47
	v_lshl_add_u64 v[220:221], s[34:35], 0, v[204:205]
	global_load_lds_dwordx4 v[220:221], off
	s_add_i32 m0, s41, 0x17f80
	ds_read_b128 v[164:167], v253 offset:49152
	ds_read_b128 v[168:171], v253 offset:50176
	ds_read_b128 v[172:175], v253 offset:51200
	ds_read_b128 v[176:179], v253 offset:52224
	ds_read_b128 v[180:183], v253 offset:53248
	ds_read_b128 v[184:187], v253 offset:54272
	ds_read_b128 v[188:191], v253 offset:55296
	ds_read_b128 v[192:195], v253 offset:56320
	global_load_lds_dwordx4 v[212:213], off offset:128
	s_add_i32 m0, s41, 0x19f80
	s_add_u32 s28, s28, 0x100
	s_addc_u32 s29, s29, 0
	global_load_lds_dwordx4 v[214:215], off offset:128
	s_add_i32 m0, s41, 0x1bf80
	s_add_u32 s27, s27, 0x100
	s_addc_u32 s44, s44, 0
	global_load_lds_dwordx4 v[244:245], off offset:128
	s_add_i32 m0, s41, 0x1df80
	s_cmp_eq_u32 s45, 12
	global_load_lds_dwordx4 v[246:247], off offset:128
	s_cbranch_scc0 .Lks4_1
	s_add_i32 m0, s49, 0xffffff80
	s_nop 0
	global_load_lds_dwordx4 v[216:217], off offset:128
	s_add_i32 m0, s50, 0xffffff80
	s_nop 0
	global_load_lds_dwordx4 v[218:219], off offset:128

; #define PG8_STAGE(bufoff, gbase, voff) do { _Pragma("unroll") for (int _i = 0; _i < 2; ++_i) \
;         __builtin_amdgcn_global_load_lds((const unsigned*)((const char*)(gbase) + (voff)[_i]), (PG8_LAS unsigned*)(lds + (bufoff) + ldsw + _i * 8192), 16, 0, 0); } while (0)
; #define PG8_LDA(dst, b, h) do { _Pragma("unroll") for (int m = 0; m < 4; ++m) _Pragma("unroll") for (int k = 0; k < 2; ++k) dst[m][k] = *(const PG8_LAS bf16x8*)(lds + PG8_SA(b, h) + aoff + m * 2048 + k * 1024); } while (0)
; #define PG8_LDB(dst, b, h) do { _Pragma("unroll") for (int n = 0; n < 2; ++n) _Pragma("unroll") for (int k = 0; k < 2; ++k) dst[n][k] = *(const PG8_LAS bf16x8*)(lds + PG8_SB(b, h) + boff + n * 2048 + k * 1024); } while (0)
; #define PG8_MMA(ai, bj, At, Bt) do { __builtin_amdgcn_s_setprio(1); _Pragma("unroll") for (int m = 0; m < 4; ++m) _Pragma("unroll") for (int n = 0; n < 2; ++n) _Pragma("unroll") for (int k = 0; k < 2; ++k) \
;         acc[ai][bj][m][n] = __builtin_amdgcn_mfma_f32_16x16x32_bf16(Bt[n][k], At[m][k], acc[ai][bj][m][n], 0, 0, 0); __builtin_amdgcn_s_setprio(0); } while (0)
; #define PG8_WAIT_V(n) asm volatile("s_waitcnt vmcnt(" #n ")" ::: "memory")
; #define PG8_WAIT_L(n) asm volatile("s_waitcnt lgkmcnt(" #n ")" ::: "memory")
; #define PG8_BAR __builtin_amdgcn_s_barrier()
; #define PG8_SCHED __builtin_amdgcn_sched_barrier(0)
; template <class Epi, class Sched, bool ALIGN_EPI = false, bool SP2 = false>
; __device__ __forceinline__ void gemm_phase(PG8_LAS unsigned char* lds, const Gemm g, const Sched& S, const Epi& E) {
;     ...
;             PG8_LDB(B0, 1, 0); PG8_LDB(B1, 1, 1); PG8_SCHED; PG8_LDA(At, 1, 0); PG8_STAGE(PG8_SA(0, 1), a2 + hstep, voffA);
;             PG8_WAIT_V(8); PG8_WAIT_L(0); PG8_BAR; PG8_MMA(0, 0, At, B0); PG8_MMA(0, 1, At, B1); PG8_BAR; PG8_SCHED;
;             PG8_LDA(At, 1, 1); PG8_STAGE(PG8_SB(1, 0), b3, voffB); PG8_STAGE(PG8_SB(1, 1), b3 + hstep, voffB); PG8_STAGE(PG8_SA(1, 0), a3, voffA);
;             PG8_WAIT_V(8); PG8_WAIT_L(0); PG8_BAR; PG8_MMA(1, 0, At, B0); PG8_MMA(1, 1, At, B1); PG8_BAR; PG8_SCHED;
.Lkmid_2:
	ds_read_b128 v[144:147], v164 offset:32768
	ds_read_b128 v[148:151], v164 offset:33792
	ds_read_b128 v[152:155], v164 offset:34816
	ds_read_b128 v[156:159], v164 offset:35840
	ds_read_b128 v[160:163], v164 offset:49152
	ds_read_b128 v[168:171], v164 offset:50176
	ds_read_b128 v[172:175], v164 offset:51200
	ds_read_b128 v[176:179], v164 offset:52224
	s_mov_b32 m0, s37
	s_add_u32 s26, s26, 0x40000
	s_addc_u32 s27, s27, 0
	global_load_lds_dwordx4 v[220:221], off
	s_mov_b32 m0, s38
	v_lshl_add_u64 v[224:225], s[26:27], 0, v[136:137]
	global_load_lds_dwordx4 v[222:223], off
	s_mov_b32 m0, s39
	ds_read_b128 v[180:183], v166 offset:32768
	ds_read_b128 v[184:187], v166 offset:33792
	ds_read_b128 v[188:191], v166 offset:34816
	ds_read_b128 v[192:195], v166 offset:35840
	ds_read_b128 v[202:205], v166 offset:36864
	ds_read_b128 v[206:209], v166 offset:37888
	ds_read_b128 v[210:213], v166 offset:38912
	ds_read_b128 v[214:217], v166 offset:39936
	global_load_lds_dwordx4 v[224:225], off
	s_waitcnt vmcnt(7) lgkmcnt(0)
	s_barrier
	s_setprio 1
	v_mfma_f32_16x16x32_bf16 v[128:131], v[144:147], v[180:183], v[128:131]
	v_mfma_f32_16x16x32_bf16 v[120:123], v[152:155], v[180:183], v[120:123]
	v_mfma_f32_16x16x32_bf16 v[112:115], v[144:147], v[188:191], v[112:115]
	v_mfma_f32_16x16x32_bf16 v[104:107], v[152:155], v[188:191], v[104:107]
	v_mfma_f32_16x16x32_bf16 v[96:99], v[144:147], v[202:205], v[96:99]
	v_mfma_f32_16x16x32_bf16 v[88:91], v[152:155], v[202:205], v[88:91]
	v_mfma_f32_16x16x32_bf16 v[80:83], v[144:147], v[210:213], v[80:83]
	v_mfma_f32_16x16x32_bf16 v[72:75], v[152:155], v[210:213], v[72:75]
	v_mfma_f32_16x16x32_bf16 v[128:131], v[148:151], v[184:187], v[128:131]
	v_mfma_f32_16x16x32_bf16 v[120:123], v[156:159], v[184:187], v[120:123]
	v_mfma_f32_16x16x32_bf16 v[112:115], v[148:151], v[192:195], v[112:115]
	v_mfma_f32_16x16x32_bf16 v[104:107], v[156:159], v[192:195], v[104:107]
	v_mfma_f32_16x16x32_bf16 v[96:99], v[148:151], v[206:209], v[96:99]
	v_mfma_f32_16x16x32_bf16 v[88:91], v[156:159], v[206:209], v[88:91]
	v_mfma_f32_16x16x32_bf16 v[80:83], v[148:151], v[214:217], v[80:83]
	v_mfma_f32_16x16x32_bf16 v[72:75], v[156:159], v[214:217], v[72:75]
	s_setprio 0
	s_setprio 1
	v_mfma_f32_16x16x32_bf16 v[124:127], v[160:163], v[180:183], v[124:127]
	v_mfma_f32_16x16x32_bf16 v[116:119], v[172:175], v[180:183], v[116:119]
	v_mfma_f32_16x16x32_bf16 v[108:111], v[160:163], v[188:191], v[108:111]
	v_mfma_f32_16x16x32_bf16 v[100:103], v[172:175], v[188:191], v[100:103]
	v_mfma_f32_16x16x32_bf16 v[92:95], v[160:163], v[202:205], v[92:95]
	v_mfma_f32_16x16x32_bf16 v[84:87], v[172:175], v[202:205], v[84:87]
	v_mfma_f32_16x16x32_bf16 v[76:79], v[160:163], v[210:213], v[76:79]
	v_mfma_f32_16x16x32_bf16 v[68:71], v[172:175], v[210:213], v[68:71]
	v_mfma_f32_16x16x32_bf16 v[124:127], v[168:171], v[184:187], v[124:127]
	v_mfma_f32_16x16x32_bf16 v[116:119], v[176:179], v[184:187], v[116:119]
	v_mfma_f32_16x16x32_bf16 v[108:111], v[168:171], v[192:195], v[108:111]
	v_mfma_f32_16x16x32_bf16 v[100:103], v[176:179], v[192:195], v[100:103]
	v_mfma_f32_16x16x32_bf16 v[92:95], v[168:171], v[206:209], v[92:95]
	v_mfma_f32_16x16x32_bf16 v[84:87], v[176:179], v[206:209], v[84:87]
	v_mfma_f32_16x16x32_bf16 v[76:79], v[168:171], v[214:217], v[76:79]
	v_mfma_f32_16x16x32_bf16 v[68:71], v[176:179], v[214:217], v[68:71]
	s_setprio 0
	s_barrier
	s_mov_b32 m0, s40
	v_lshl_add_u64 v[224:225], s[26:27], 0, v[132:133]
	global_load_lds_dwordx4 v[224:225], off
	s_add_i32 m0, s35, 0x17f80
	ds_read_b128 v[180:183], v166 offset:49152
	ds_read_b128 v[184:187], v166 offset:50176
	ds_read_b128 v[188:191], v166 offset:51200
	ds_read_b128 v[192:195], v166 offset:52224
	ds_read_b128 v[202:205], v166 offset:53248
	ds_read_b128 v[206:209], v166 offset:54272
	ds_read_b128 v[210:213], v166 offset:55296
	ds_read_b128 v[214:217], v166 offset:56320
	global_load_lds_dwordx4 v[198:199], off offset:128
	s_add_i32 m0, s35, 0x19f80
	s_add_u32 s8, s8, 0x100
	s_addc_u32 s9, s9, 0
	global_load_lds_dwordx4 v[218:219], off offset:128
	s_add_i32 m0, s35, 0x1bf80
	s_add_u32 s44, s44, 0x100
	s_addc_u32 s45, s45, 0
	global_load_lds_dwordx4 v[244:245], off offset:128
	s_add_i32 m0, s35, 0x1df80
	s_cmp_eq_u32 s46, 12
	global_load_lds_dwordx4 v[246:247], off offset:128
	s_cbranch_scc0 .Lks4_2
	s_add_i32 m0, s41, 0xffffff80
	s_nop 0
	global_load_lds_dwordx4 v[220:221], off offset:128
	s_add_i32 m0, s42, 0xffffff80
	s_nop 0
	global_load_lds_dwordx4 v[222:223], off offset:128

; #define PG8_STAGE(bufoff, gbase, voff) do { _Pragma("unroll") for (int _i = 0; _i < 2; ++_i) \
;         __builtin_amdgcn_global_load_lds((const unsigned*)((const char*)(gbase) + (voff)[_i]), (PG8_LAS unsigned*)(lds + (bufoff) + ldsw + _i * 8192), 16, 0, 0); } while (0)
; #define PG8_LDA(dst, b, h) do { _Pragma("unroll") for (int m = 0; m < 4; ++m) _Pragma("unroll") for (int k = 0; k < 2; ++k) dst[m][k] = *(const PG8_LAS bf16x8*)(lds + PG8_SA(b, h) + aoff + m * 2048 + k * 1024); } while (0)
; #define PG8_LDB(dst, b, h) do { _Pragma("unroll") for (int n = 0; n < 2; ++n) _Pragma("unroll") for (int k = 0; k < 2; ++k) dst[n][k] = *(const PG8_LAS bf16x8*)(lds + PG8_SB(b, h) + boff + n * 2048 + k * 1024); } while (0)
; #define PG8_MMA(ai, bj, At, Bt) do { __builtin_amdgcn_s_setprio(1); _Pragma("unroll") for (int m = 0; m < 4; ++m) _Pragma("unroll") for (int n = 0; n < 2; ++n) _Pragma("unroll") for (int k = 0; k < 2; ++k) \
;         acc[ai][bj][m][n] = __builtin_amdgcn_mfma_f32_16x16x32_bf16(Bt[n][k], At[m][k], acc[ai][bj][m][n], 0, 0, 0); __builtin_amdgcn_s_setprio(0); } while (0)
; #define PG8_WAIT_V(n) asm volatile("s_waitcnt vmcnt(" #n ")" ::: "memory")
; #define PG8_WAIT_L(n) asm volatile("s_waitcnt lgkmcnt(" #n ")" ::: "memory")
; #define PG8_BAR __builtin_amdgcn_s_barrier()
; #define PG8_SCHED __builtin_amdgcn_sched_barrier(0)
; template <class Epi, class Sched, bool ALIGN_EPI = false, bool SP2 = false>
; __device__ __forceinline__ void gemm_phase(PG8_LAS unsigned char* lds, const Gemm g, const Sched& S, const Epi& E) {
;     ...
;             PG8_LDB(B0, 1, 0); PG8_LDB(B1, 1, 1); PG8_SCHED; PG8_LDA(At, 1, 0); PG8_STAGE(PG8_SA(0, 1), a2 + hstep, voffA);
;             PG8_WAIT_V(8); PG8_WAIT_L(0); PG8_BAR; PG8_MMA(0, 0, At, B0); PG8_MMA(0, 1, At, B1); PG8_BAR; PG8_SCHED;
;             PG8_LDA(At, 1, 1); PG8_STAGE(PG8_SB(1, 0), b3, voffB); PG8_STAGE(PG8_SB(1, 1), b3 + hstep, voffB); PG8_STAGE(PG8_SA(1, 0), a3, voffA);
;             PG8_WAIT_V(8); PG8_WAIT_L(0); PG8_BAR; PG8_MMA(1, 0, At, B0); PG8_MMA(1, 1, At, B1); PG8_BAR; PG8_SCHED;
.Lkmid_3:
	ds_read_b128 v[68:71], v234 offset:32768
	ds_read_b128 v[80:83], v234 offset:33792
	ds_read_b128 v[92:95], v234 offset:34816
	ds_read_b128 v[100:103], v234 offset:35840
	ds_read_b128 v[112:115], v234 offset:49152
	ds_read_b128 v[120:123], v234 offset:50176
	ds_read_b128 v[132:135], v234 offset:51200
	ds_read_b128 v[144:147], v234 offset:52224
	s_mov_b32 m0, s40
	s_add_u32 s26, s30, 0xb0000
	s_addc_u32 s27, s31, 0
	global_load_lds_dwordx4 v[214:215], off
	s_mov_b32 m0, s41
	v_lshl_add_u64 v[218:219], s[26:27], 0, v[0:1]
	global_load_lds_dwordx4 v[216:217], off
	s_mov_b32 m0, s42
	ds_read_b128 v[156:159], v236 offset:32768
	ds_read_b128 v[168:171], v236 offset:33792
	ds_read_b128 v[172:175], v236 offset:34816
	ds_read_b128 v[176:179], v236 offset:35840
	ds_read_b128 v[180:183], v236 offset:36864
	ds_read_b128 v[184:187], v236 offset:37888
	ds_read_b128 v[188:191], v236 offset:38912
	ds_read_b128 v[208:211], v236 offset:39936
	global_load_lds_dwordx4 v[218:219], off
	s_waitcnt vmcnt(7) lgkmcnt(0)
	s_barrier
	s_setprio 1
	v_mfma_f32_16x16x32_bf16 v[164:167], v[68:71], v[156:159], v[164:167]
	v_mfma_f32_16x16x32_bf16 v[160:163], v[92:95], v[156:159], v[160:163]
	v_mfma_f32_16x16x32_bf16 v[140:143], v[68:71], v[172:175], v[140:143]
	v_mfma_f32_16x16x32_bf16 v[136:139], v[92:95], v[172:175], v[136:139]
	v_mfma_f32_16x16x32_bf16 v[116:119], v[68:71], v[180:183], v[116:119]
	v_mfma_f32_16x16x32_bf16 v[108:111], v[92:95], v[180:183], v[108:111]
	v_mfma_f32_16x16x32_bf16 v[88:91], v[68:71], v[188:191], v[88:91]
	v_mfma_f32_16x16x32_bf16 v[84:87], v[92:95], v[188:191], v[84:87]
	v_mfma_f32_16x16x32_bf16 v[164:167], v[80:83], v[168:171], v[164:167]
	v_mfma_f32_16x16x32_bf16 v[160:163], v[100:103], v[168:171], v[160:163]
	v_mfma_f32_16x16x32_bf16 v[140:143], v[80:83], v[176:179], v[140:143]
	v_mfma_f32_16x16x32_bf16 v[136:139], v[100:103], v[176:179], v[136:139]
	v_mfma_f32_16x16x32_bf16 v[116:119], v[80:83], v[184:187], v[116:119]
	v_mfma_f32_16x16x32_bf16 v[108:111], v[100:103], v[184:187], v[108:111]
	v_mfma_f32_16x16x32_bf16 v[88:91], v[80:83], v[208:211], v[88:91]
	v_mfma_f32_16x16x32_bf16 v[84:87], v[100:103], v[208:211], v[84:87]
	s_setprio 0
	s_setprio 1
	v_mfma_f32_16x16x32_bf16 v[152:155], v[112:115], v[156:159], v[152:155]
	v_mfma_f32_16x16x32_bf16 v[148:151], v[132:135], v[156:159], v[148:151]
	v_mfma_f32_16x16x32_bf16 v[128:131], v[112:115], v[172:175], v[128:131]
	v_mfma_f32_16x16x32_bf16 v[124:127], v[132:135], v[172:175], v[124:127]
	v_mfma_f32_16x16x32_bf16 v[104:107], v[112:115], v[180:183], v[104:107]
	v_mfma_f32_16x16x32_bf16 v[96:99], v[132:135], v[180:183], v[96:99]
	v_mfma_f32_16x16x32_bf16 v[76:79], v[112:115], v[188:191], v[76:79]
	v_mfma_f32_16x16x32_bf16 v[72:75], v[132:135], v[188:191], v[72:75]
	v_mfma_f32_16x16x32_bf16 v[152:155], v[120:123], v[168:171], v[152:155]
	v_mfma_f32_16x16x32_bf16 v[148:151], v[144:147], v[168:171], v[148:151]
	v_mfma_f32_16x16x32_bf16 v[128:131], v[120:123], v[176:179], v[128:131]
	v_mfma_f32_16x16x32_bf16 v[124:127], v[144:147], v[176:179], v[124:127]
	v_mfma_f32_16x16x32_bf16 v[104:107], v[120:123], v[184:187], v[104:107]
	v_mfma_f32_16x16x32_bf16 v[96:99], v[144:147], v[184:187], v[96:99]
	v_mfma_f32_16x16x32_bf16 v[76:79], v[120:123], v[208:211], v[76:79]
	v_mfma_f32_16x16x32_bf16 v[72:75], v[144:147], v[208:211], v[72:75]
	s_setprio 0
	s_barrier
	s_mov_b32 m0, s43
	v_lshl_add_u64 v[218:219], s[26:27], 0, v[194:195]
	global_load_lds_dwordx4 v[218:219], off
	s_add_i32 m0, s39, 0x17f80
	ds_read_b128 v[156:159], v236 offset:49152
	ds_read_b128 v[168:171], v236 offset:50176
	ds_read_b128 v[172:175], v236 offset:51200
	ds_read_b128 v[176:179], v236 offset:52224
	ds_read_b128 v[180:183], v236 offset:53248
	ds_read_b128 v[184:187], v236 offset:54272
	ds_read_b128 v[188:191], v236 offset:55296
	ds_read_b128 v[208:211], v236 offset:56320
	global_load_lds_dwordx4 v[198:199], off offset:128
	s_add_i32 m0, s39, 0x19f80
	s_mov_b64 s[26:27], s[8:9]
	global_load_lds_dwordx4 v[212:213], off offset:128
	s_add_i32 m0, s39, 0x1bf80
	s_add_u32 s44, s44, 0x100
	s_addc_u32 s45, s45, 0
	global_load_lds_dwordx4 v[244:245], off offset:128
	s_add_i32 m0, s39, 0x1df80
	s_cmp_eq_u32 s53, 40
	global_load_lds_dwordx4 v[246:247], off offset:128
	s_cbranch_scc0 .Lks4_3
	s_add_i32 m0, s47, 0xffffff80
	s_nop 0
	global_load_lds_dwordx4 v[214:215], off offset:128
	s_add_i32 m0, s48, 0xffffff80
	s_nop 0
	global_load_lds_dwordx4 v[216:217], off offset:128
